# phase-1 k_r rotary epilogue: cos/sin loaded one 16-row step ahead into spare VGPRs, counted vmcnt(3) instead of vmcnt(0)
# speedup vs baseline: 1.0378x; 1.0048x over previous
.LBB0_212:
	s_or_b64 exec, exec, s[8:9]
	s_andn2_b64 vcc, exec, s[54:55]
	s_cbranch_vccnz .LBB0_214
	v_lshlrev_b32_e32 v244, 6, v150
	v_and_b32_e32 v244, 0x1ffc0, v244
	v_mov_b32_e32 v245, 0
	v_lshl_add_u64 v[248:249], v[142:143], 0, v[244:245]
	global_load_dwordx4 v[232:235], v[248:249], off offset:1040
	global_load_dwordx4 v[236:239], v[248:249], off offset:1024
	v_lshl_add_u64 v[248:249], v[140:141], 0, v[244:245]
	global_load_dwordx4 v[240:243], v[248:249], off offset:1024
	global_load_dwordx4 v[252:255], v[248:249], off offset:1040
	v_mov_b32_e32 v138, v162
	s_waitcnt lgkmcnt(0)
	v_mov_b32_e32 v151, v162
	v_mov_b32_e32 v153, v172
	v_mov_b32_e32 v155, v172
	v_mov_b32_e32 v157, v163
	v_mov_b32_e32 v175, v163
	v_mov_b32_e32 v200, v173
	v_mov_b32_e32 v201, v173
	v_mov_b32_e32 v202, v158
	v_mov_b32_e32 v203, v158
	v_mov_b32_e32 v204, v170
	v_mov_b32_e32 v205, v170
	v_mov_b32_e32 v206, v159
	v_mov_b32_e32 v207, v159
	v_mov_b32_e32 v210, v171
	v_mov_b32_e32 v211, v171
	v_permlane32_swap_b32_e32 v138, v151
	v_permlane32_swap_b32_e32 v153, v155
	v_permlane32_swap_b32_e32 v157, v175
	v_permlane32_swap_b32_e32 v200, v201
	v_permlane32_swap_b32_e32 v202, v203
	v_permlane32_swap_b32_e32 v204, v205
	v_permlane32_swap_b32_e32 v206, v207
	v_permlane32_swap_b32_e32 v210, v211
	v_cndmask_b32_e64 v156, v138, v151, s[4:5]
	v_cndmask_b32_e64 v174, v153, v155, s[4:5]
	v_cndmask_b32_e64 v157, v157, v175, s[4:5]
	v_cndmask_b32_e64 v175, v200, v201, s[4:5]
	v_cndmask_b32_e64 v200, v202, v203, s[4:5]
	v_cndmask_b32_e64 v202, v204, v205, s[4:5]
	v_cndmask_b32_e64 v201, v206, v207, s[4:5]
	v_cndmask_b32_e64 v203, v210, v211, s[4:5]
	s_waitcnt vmcnt(0)
	v_xor_b32_e32 v138, 0x80000000, v232
	v_xor_b32_e32 v151, 0x80000000, v233
	v_xor_b32_e32 v153, 0x80000000, v234
	v_xor_b32_e32 v155, 0x80000000, v235
	v_xor_b32_e32 v204, 0x80000000, v236
	v_xor_b32_e32 v205, 0x80000000, v237
	v_xor_b32_e32 v206, 0x80000000, v238
	v_xor_b32_e32 v207, 0x80000000, v239
	v_cndmask_b32_e64 v235, v235, v155, s[4:5]
	v_cndmask_b32_e64 v234, v234, v153, s[4:5]
	v_cndmask_b32_e64 v233, v233, v151, s[4:5]
	v_cndmask_b32_e64 v232, v232, v138, s[4:5]
	v_cndmask_b32_e64 v239, v239, v207, s[4:5]
	v_cndmask_b32_e64 v238, v238, v206, s[4:5]
	v_cndmask_b32_e64 v237, v237, v205, s[4:5]
	v_cndmask_b32_e64 v236, v236, v204, s[4:5]
	v_pk_mul_f32 v[156:157], v[236:237], v[156:157]
	v_pk_mul_f32 v[236:237], v[238:239], v[200:201]
	v_pk_mul_f32 v[174:175], v[232:233], v[174:175]
	v_pk_mul_f32 v[232:233], v[234:235], v[202:203]
	v_pk_fma_f32 v[158:159], v[158:159], v[242:243], v[236:237]
	v_pk_fma_f32 v[162:163], v[162:163], v[240:241], v[156:157]
	v_pk_fma_f32 v[170:171], v[170:171], v[254:255], v[232:233]
	v_pk_fma_f32 v[172:173], v[172:173], v[252:253], v[174:175]
	v_add_u32_e32 v244, 16, v150
	v_lshlrev_b32_e32 v244, 6, v244
	v_and_b32_e32 v244, 0x1ffc0, v244
	v_mov_b32_e32 v245, 0
	v_lshl_add_u64 v[248:249], v[142:143], 0, v[244:245]
	global_load_dwordx4 v[232:235], v[248:249], off offset:1040
	global_load_dwordx4 v[236:239], v[248:249], off offset:1024
	v_lshl_add_u64 v[248:249], v[140:141], 0, v[244:245]
	global_load_dwordx4 v[240:243], v[248:249], off offset:1024
	global_load_dwordx4 v[252:255], v[248:249], off offset:1040

.LBB0_221:
	s_or_b64 exec, exec, s[56:57]
	s_andn2_b64 vcc, exec, s[54:55]
	s_cbranch_vccnz .LBB0_223
	v_mov_b32_e32 v138, v162
	s_waitcnt lgkmcnt(0)
	v_mov_b32_e32 v151, v162
	v_mov_b32_e32 v153, v172
	v_mov_b32_e32 v175, v172
	v_mov_b32_e32 v201, v163
	v_mov_b32_e32 v203, v163
	v_mov_b32_e32 v204, v173
	v_mov_b32_e32 v205, v173
	v_mov_b32_e32 v206, v158
	v_mov_b32_e32 v207, v158
	v_mov_b32_e32 v210, v170
	v_mov_b32_e32 v211, v170
	v_mov_b32_e32 v212, v159
	v_mov_b32_e32 v213, v159
	v_mov_b32_e32 v214, v171
	v_mov_b32_e32 v215, v171
	v_permlane32_swap_b32_e32 v138, v151
	v_permlane32_swap_b32_e32 v153, v175
	v_permlane32_swap_b32_e32 v201, v203
	v_permlane32_swap_b32_e32 v204, v205
	v_permlane32_swap_b32_e32 v206, v207
	v_permlane32_swap_b32_e32 v210, v211
	v_permlane32_swap_b32_e32 v212, v213
	v_permlane32_swap_b32_e32 v214, v215
	v_cndmask_b32_e64 v200, v138, v151, s[4:5]
	v_cndmask_b32_e64 v202, v153, v175, s[4:5]
	v_cndmask_b32_e64 v201, v201, v203, s[4:5]
	v_cndmask_b32_e64 v203, v204, v205, s[4:5]
	v_cndmask_b32_e64 v204, v206, v207, s[4:5]
	v_cndmask_b32_e64 v206, v210, v211, s[4:5]
	v_cndmask_b32_e64 v205, v212, v213, s[4:5]
	v_cndmask_b32_e64 v207, v214, v215, s[4:5]
	s_waitcnt vmcnt(3)
	v_xor_b32_e32 v138, 0x80000000, v232
	v_xor_b32_e32 v151, 0x80000000, v233
	v_xor_b32_e32 v153, 0x80000000, v234
	v_xor_b32_e32 v175, 0x80000000, v235
	v_xor_b32_e32 v210, 0x80000000, v236
	v_xor_b32_e32 v211, 0x80000000, v237
	v_xor_b32_e32 v212, 0x80000000, v238
	v_xor_b32_e32 v213, 0x80000000, v239
	v_cndmask_b32_e64 v235, v235, v175, s[4:5]
	v_cndmask_b32_e64 v234, v234, v153, s[4:5]
	v_cndmask_b32_e64 v233, v233, v151, s[4:5]
	v_cndmask_b32_e64 v232, v232, v138, s[4:5]
	v_cndmask_b32_e64 v239, v239, v213, s[4:5]
	v_cndmask_b32_e64 v238, v238, v212, s[4:5]
	v_cndmask_b32_e64 v237, v237, v211, s[4:5]
	v_cndmask_b32_e64 v236, v236, v210, s[4:5]
	v_pk_mul_f32 v[236:237], v[236:237], v[200:201]
	v_pk_mul_f32 v[238:239], v[238:239], v[204:205]
	v_pk_mul_f32 v[232:233], v[232:233], v[202:203]
	v_pk_mul_f32 v[234:235], v[234:235], v[206:207]
	v_pk_fma_f32 v[158:159], v[158:159], v[242:243], v[238:239]
	v_pk_fma_f32 v[162:163], v[162:163], v[240:241], v[236:237]
	v_pk_fma_f32 v[170:171], v[170:171], v[254:255], v[234:235]
	v_pk_fma_f32 v[172:173], v[172:173], v[252:253], v[232:233]
	v_add_u32_e32 v244, 16, v174
	v_lshlrev_b32_e32 v244, 6, v244
	v_and_b32_e32 v244, 0x1ffc0, v244
	v_mov_b32_e32 v245, 0
	v_lshl_add_u64 v[248:249], v[142:143], 0, v[244:245]
	global_load_dwordx4 v[232:235], v[248:249], off offset:1040
	global_load_dwordx4 v[236:239], v[248:249], off offset:1024
	v_lshl_add_u64 v[248:249], v[140:141], 0, v[244:245]
	global_load_dwordx4 v[240:243], v[248:249], off offset:1024
	global_load_dwordx4 v[252:255], v[248:249], off offset:1040

.LBB0_239:
	s_or_b64 exec, exec, s[56:57]
	s_andn2_b64 vcc, exec, s[54:55]
	s_cbranch_vccnz .LBB0_241
	v_mov_b32_e32 v138, v162
	s_waitcnt lgkmcnt(0)
	v_mov_b32_e32 v151, v162
	v_mov_b32_e32 v153, v172
	v_mov_b32_e32 v175, v172
	v_mov_b32_e32 v201, v163
	v_mov_b32_e32 v203, v163
	v_mov_b32_e32 v204, v173
	v_mov_b32_e32 v205, v173
	v_mov_b32_e32 v206, v158
	v_mov_b32_e32 v207, v158
	v_mov_b32_e32 v210, v170
	v_mov_b32_e32 v211, v170
	v_mov_b32_e32 v212, v159
	v_mov_b32_e32 v213, v159
	v_mov_b32_e32 v214, v171
	v_mov_b32_e32 v215, v171
	v_permlane32_swap_b32_e32 v138, v151
	v_permlane32_swap_b32_e32 v153, v175
	v_permlane32_swap_b32_e32 v201, v203
	v_permlane32_swap_b32_e32 v204, v205
	v_permlane32_swap_b32_e32 v206, v207
	v_permlane32_swap_b32_e32 v210, v211
	v_permlane32_swap_b32_e32 v212, v213
	v_permlane32_swap_b32_e32 v214, v215
	v_cndmask_b32_e64 v200, v138, v151, s[4:5]
	v_cndmask_b32_e64 v202, v153, v175, s[4:5]
	v_cndmask_b32_e64 v201, v201, v203, s[4:5]
	v_cndmask_b32_e64 v203, v204, v205, s[4:5]
	v_cndmask_b32_e64 v204, v206, v207, s[4:5]
	v_cndmask_b32_e64 v206, v210, v211, s[4:5]
	v_cndmask_b32_e64 v205, v212, v213, s[4:5]
	v_cndmask_b32_e64 v207, v214, v215, s[4:5]
	s_waitcnt vmcnt(3)
	v_xor_b32_e32 v138, 0x80000000, v232
	v_xor_b32_e32 v151, 0x80000000, v233
	v_xor_b32_e32 v153, 0x80000000, v234
	v_xor_b32_e32 v175, 0x80000000, v235
	v_xor_b32_e32 v210, 0x80000000, v236
	v_xor_b32_e32 v211, 0x80000000, v237
	v_xor_b32_e32 v212, 0x80000000, v238
	v_xor_b32_e32 v213, 0x80000000, v239
	v_cndmask_b32_e64 v235, v235, v175, s[4:5]
	v_cndmask_b32_e64 v234, v234, v153, s[4:5]
	v_cndmask_b32_e64 v233, v233, v151, s[4:5]
	v_cndmask_b32_e64 v232, v232, v138, s[4:5]
	v_cndmask_b32_e64 v239, v239, v213, s[4:5]
	v_cndmask_b32_e64 v238, v238, v212, s[4:5]
	v_cndmask_b32_e64 v237, v237, v211, s[4:5]
	v_cndmask_b32_e64 v236, v236, v210, s[4:5]
	v_pk_mul_f32 v[236:237], v[236:237], v[200:201]
	v_pk_mul_f32 v[238:239], v[238:239], v[204:205]
	v_pk_mul_f32 v[232:233], v[232:233], v[202:203]
	v_pk_mul_f32 v[234:235], v[234:235], v[206:207]
	v_pk_fma_f32 v[158:159], v[158:159], v[242:243], v[238:239]
	v_pk_fma_f32 v[162:163], v[162:163], v[240:241], v[236:237]
	v_pk_fma_f32 v[170:171], v[170:171], v[254:255], v[234:235]
	v_pk_fma_f32 v[172:173], v[172:173], v[252:253], v[232:233]
	v_add_u32_e32 v244, 80, v174
	v_lshlrev_b32_e32 v244, 6, v244
	v_and_b32_e32 v244, 0x1ffc0, v244
	v_mov_b32_e32 v245, 0
	v_lshl_add_u64 v[248:249], v[142:143], 0, v[244:245]
	global_load_dwordx4 v[232:235], v[248:249], off offset:1040
	global_load_dwordx4 v[236:239], v[248:249], off offset:1024
	v_lshl_add_u64 v[248:249], v[140:141], 0, v[244:245]
	global_load_dwordx4 v[240:243], v[248:249], off offset:1024
	global_load_dwordx4 v[252:255], v[248:249], off offset:1040

.LBB0_248:
	s_or_b64 exec, exec, s[56:57]
	s_andn2_b64 vcc, exec, s[54:55]
	s_cbranch_vccnz .LBB0_250
	v_mov_b32_e32 v138, v164
	s_waitcnt lgkmcnt(0)
	v_mov_b32_e32 v151, v164
	v_mov_b32_e32 v153, v174
	v_mov_b32_e32 v159, v174
	v_mov_b32_e32 v201, v165
	v_mov_b32_e32 v203, v165
	v_mov_b32_e32 v204, v175
	v_mov_b32_e32 v205, v175
	v_mov_b32_e32 v206, v160
	v_mov_b32_e32 v207, v160
	v_mov_b32_e32 v210, v172
	v_mov_b32_e32 v211, v172
	v_mov_b32_e32 v212, v161
	v_mov_b32_e32 v213, v161
	v_mov_b32_e32 v214, v173
	v_mov_b32_e32 v215, v173
	v_permlane32_swap_b32_e32 v138, v151
	v_permlane32_swap_b32_e32 v153, v159
	v_permlane32_swap_b32_e32 v201, v203
	v_permlane32_swap_b32_e32 v204, v205
	v_permlane32_swap_b32_e32 v206, v207
	v_permlane32_swap_b32_e32 v210, v211
	v_permlane32_swap_b32_e32 v212, v213
	v_permlane32_swap_b32_e32 v214, v215
	v_cndmask_b32_e64 v200, v138, v151, s[4:5]
	v_cndmask_b32_e64 v202, v153, v159, s[4:5]
	v_cndmask_b32_e64 v201, v201, v203, s[4:5]
	v_cndmask_b32_e64 v203, v204, v205, s[4:5]
	v_cndmask_b32_e64 v204, v206, v207, s[4:5]
	v_cndmask_b32_e64 v206, v210, v211, s[4:5]
	v_cndmask_b32_e64 v205, v212, v213, s[4:5]
	v_cndmask_b32_e64 v207, v214, v215, s[4:5]
	s_waitcnt vmcnt(3)
	v_xor_b32_e32 v138, 0x80000000, v232
	v_xor_b32_e32 v151, 0x80000000, v233
	v_xor_b32_e32 v153, 0x80000000, v234
	v_xor_b32_e32 v159, 0x80000000, v235
	v_xor_b32_e32 v210, 0x80000000, v236
	v_xor_b32_e32 v211, 0x80000000, v237
	v_xor_b32_e32 v212, 0x80000000, v238
	v_xor_b32_e32 v213, 0x80000000, v239
	v_cndmask_b32_e64 v235, v235, v159, s[4:5]
	v_cndmask_b32_e64 v234, v234, v153, s[4:5]
	v_cndmask_b32_e64 v233, v233, v151, s[4:5]
	v_cndmask_b32_e64 v232, v232, v138, s[4:5]
	v_cndmask_b32_e64 v239, v239, v213, s[4:5]
	v_cndmask_b32_e64 v238, v238, v212, s[4:5]
	v_cndmask_b32_e64 v237, v237, v211, s[4:5]
	v_cndmask_b32_e64 v236, v236, v210, s[4:5]
	v_pk_mul_f32 v[236:237], v[236:237], v[200:201]
	v_pk_mul_f32 v[238:239], v[238:239], v[204:205]
	v_pk_mul_f32 v[232:233], v[232:233], v[202:203]
	v_pk_mul_f32 v[234:235], v[234:235], v[206:207]
	v_pk_fma_f32 v[160:161], v[160:161], v[242:243], v[238:239]
	v_pk_fma_f32 v[164:165], v[164:165], v[240:241], v[236:237]
	v_pk_fma_f32 v[172:173], v[172:173], v[254:255], v[234:235]
	v_pk_fma_f32 v[174:175], v[174:175], v[252:253], v[232:233]
	v_add_u32_e32 v244, 16, v158
	v_lshlrev_b32_e32 v244, 6, v244
	v_and_b32_e32 v244, 0x1ffc0, v244
	v_mov_b32_e32 v245, 0
	v_lshl_add_u64 v[248:249], v[142:143], 0, v[244:245]
	global_load_dwordx4 v[232:235], v[248:249], off offset:1040
	global_load_dwordx4 v[236:239], v[248:249], off offset:1024
	v_lshl_add_u64 v[248:249], v[140:141], 0, v[244:245]
	global_load_dwordx4 v[240:243], v[248:249], off offset:1024
	global_load_dwordx4 v[252:255], v[248:249], off offset:1040

.LBB0_275:
	s_or_b64 exec, exec, s[8:9]
	s_andn2_b64 vcc, exec, s[54:55]
	s_cbranch_vccnz .LBB0_277
	v_mov_b32_e32 v138, v162
	s_waitcnt lgkmcnt(0)
	v_mov_b32_e32 v151, v162
	v_mov_b32_e32 v153, v154
	v_mov_b32_e32 v173, v154
	v_mov_b32_e32 v175, v163
	v_mov_b32_e32 v201, v163
	v_mov_b32_e32 v202, v155
	v_mov_b32_e32 v203, v155
	v_mov_b32_e32 v204, v158
	v_mov_b32_e32 v205, v158
	v_mov_b32_e32 v206, v170
	v_mov_b32_e32 v207, v170
	v_mov_b32_e32 v210, v159
	v_mov_b32_e32 v211, v159
	v_mov_b32_e32 v212, v171
	v_mov_b32_e32 v213, v171
	v_permlane32_swap_b32_e32 v138, v151
	v_permlane32_swap_b32_e32 v153, v173
	v_permlane32_swap_b32_e32 v175, v201
	v_permlane32_swap_b32_e32 v202, v203
	v_permlane32_swap_b32_e32 v204, v205
	v_permlane32_swap_b32_e32 v206, v207
	v_permlane32_swap_b32_e32 v210, v211
	v_permlane32_swap_b32_e32 v212, v213
	v_cndmask_b32_e64 v174, v138, v151, s[4:5]
	v_cndmask_b32_e64 v200, v153, v173, s[4:5]
	v_cndmask_b32_e64 v175, v175, v201, s[4:5]
	v_cndmask_b32_e64 v201, v202, v203, s[4:5]
	v_cndmask_b32_e64 v202, v204, v205, s[4:5]
	v_cndmask_b32_e64 v204, v206, v207, s[4:5]
	v_cndmask_b32_e64 v203, v210, v211, s[4:5]
	v_cndmask_b32_e64 v205, v212, v213, s[4:5]
	s_waitcnt vmcnt(3)
	v_xor_b32_e32 v138, 0x80000000, v232
	v_xor_b32_e32 v151, 0x80000000, v233
	v_xor_b32_e32 v153, 0x80000000, v234
	v_xor_b32_e32 v173, 0x80000000, v235
	v_xor_b32_e32 v206, 0x80000000, v236
	v_xor_b32_e32 v207, 0x80000000, v237
	v_xor_b32_e32 v210, 0x80000000, v238
	v_xor_b32_e32 v211, 0x80000000, v239
	v_cndmask_b32_e64 v235, v235, v173, s[4:5]
	v_cndmask_b32_e64 v234, v234, v153, s[4:5]
	v_cndmask_b32_e64 v233, v233, v151, s[4:5]
	v_cndmask_b32_e64 v232, v232, v138, s[4:5]
	v_cndmask_b32_e64 v239, v239, v211, s[4:5]
	v_cndmask_b32_e64 v238, v238, v210, s[4:5]
	v_cndmask_b32_e64 v237, v237, v207, s[4:5]
	v_cndmask_b32_e64 v236, v236, v206, s[4:5]
	v_pk_mul_f32 v[174:175], v[236:237], v[174:175]
	v_pk_mul_f32 v[236:237], v[238:239], v[202:203]
	v_pk_mul_f32 v[232:233], v[232:233], v[200:201]
	v_pk_mul_f32 v[234:235], v[234:235], v[204:205]
	v_pk_fma_f32 v[158:159], v[158:159], v[242:243], v[236:237]
	v_pk_fma_f32 v[162:163], v[162:163], v[240:241], v[174:175]
	v_pk_fma_f32 v[170:171], v[170:171], v[254:255], v[234:235]
	v_pk_fma_f32 v[154:155], v[154:155], v[252:253], v[232:233]

	.amdhsa_kernel _Z6mk_fwd6Params
		.amdhsa_group_segment_fixed_size 0
		.amdhsa_private_segment_fixed_size 0
		.amdhsa_kernarg_size 384
		.amdhsa_user_sgpr_count 2
		.amdhsa_user_sgpr_dispatch_ptr 0
		.amdhsa_user_sgpr_queue_ptr 0
		.amdhsa_user_sgpr_kernarg_segment_ptr 1
		.amdhsa_user_sgpr_dispatch_id 0
		.amdhsa_user_sgpr_kernarg_preload_length 0
		.amdhsa_user_sgpr_kernarg_preload_offset 0
		.amdhsa_user_sgpr_private_segment_size 0
		.amdhsa_uses_dynamic_stack 0
		.amdhsa_enable_private_segment 0
		.amdhsa_system_sgpr_workgroup_id_x 1
		.amdhsa_system_sgpr_workgroup_id_y 0
		.amdhsa_system_sgpr_workgroup_id_z 0
		.amdhsa_system_sgpr_workgroup_info 0
		.amdhsa_system_vgpr_workitem_id 2
		.amdhsa_next_free_vgpr 256
		.amdhsa_next_free_sgpr 98
		.amdhsa_accum_offset 256
		.amdhsa_reserve_vcc 1
		.amdhsa_float_round_mode_32 0
		.amdhsa_float_round_mode_16_64 0
		.amdhsa_float_denorm_mode_32 3
		.amdhsa_float_denorm_mode_16_64 3
		.amdhsa_dx10_clamp 1
		.amdhsa_ieee_mode 1
		.amdhsa_fp16_overflow 0
		.amdhsa_tg_split 0
		.amdhsa_exception_fp_ieee_invalid_op 0
		.amdhsa_exception_fp_denorm_src 0
		.amdhsa_exception_fp_ieee_div_zero 0
		.amdhsa_exception_fp_ieee_overflow 0
		.amdhsa_exception_fp_ieee_underflow 0
		.amdhsa_exception_fp_ieee_inexact 0
		.amdhsa_exception_int_div_zero 0
	.end_amdhsa_kernel

amdhsa.kernels:
  - .agpr_count:     0
    .args:
      - .offset:         0
        .size:           128
        .value_kind:     by_value
      - .offset:         128
        .size:           4
        .value_kind:     hidden_block_count_x
      - .offset:         132
        .size:           4
        .value_kind:     hidden_block_count_y
      - .offset:         136
        .size:           4
        .value_kind:     hidden_block_count_z
      - .offset:         140
        .size:           2
        .value_kind:     hidden_group_size_x
      - .offset:         142
        .size:           2
        .value_kind:     hidden_group_size_y
      - .offset:         144
        .size:           2
        .value_kind:     hidden_group_size_z
      - .offset:         146
        .size:           2
        .value_kind:     hidden_remainder_x
      - .offset:         148
        .size:           2
        .value_kind:     hidden_remainder_y
      - .offset:         150
        .size:           2
        .value_kind:     hidden_remainder_z
      - .offset:         168
        .size:           8
        .value_kind:     hidden_global_offset_x
      - .offset:         176
        .size:           8
        .value_kind:     hidden_global_offset_y
      - .offset:         184
        .size:           8
        .value_kind:     hidden_global_offset_z
      - .offset:         192
        .size:           2
        .value_kind:     hidden_grid_dims
      - .offset:         216
        .size:           8
        .value_kind:     hidden_multigrid_sync_arg
      - .offset:         248
        .size:           4
        .value_kind:     hidden_dynamic_lds_size
    .group_segment_fixed_size: 0
    .kernarg_segment_align: 8
    .kernarg_segment_size: 384
    .language:       OpenCL C
    .language_version:
      - 2
      - 0
    .max_flat_workgroup_size: 512
    .name:           _Z6mk_fwd6Params
    .private_segment_fixed_size: 0
    .sgpr_count:     104
    .sgpr_spill_count: 86
    .symbol:         _Z6mk_fwd6Params.kd
    .uniform_work_group_size: 1
    .uses_dynamic_stack: false
    .vgpr_count:     256
    .vgpr_spill_count: 0
    .wavefront_size: 64
